# up phase: next tile's first K slab requested before the epilogue (LDS-DMA prefetch, prologue copies masked)
# baseline (speedup 1.0000x reference)
.LBB0_9:
	s_mul_hi_i32 s0, s24, 0x38e38e39
	s_lshr_b32 s1, s0, 31
	s_ashr_i32 s0, s0, 1
	s_add_i32 s2, s0, s1
	s_mul_i32 s0, s2, 9
	s_sub_i32 s4, s24, s0
	s_lshl_b32 s0, s2, 10
	s_ashr_i32 s1, s0, 31
	v_writelane_b32 v252, s0, 54
	s_nop 1
	v_writelane_b32 v252, s1, 55
	s_lshl_b32 s0, s2, 1
	s_ashr_i32 s1, s0, 31
	v_writelane_b32 v252, s0, 56
	s_nop 1
	v_writelane_b32 v252, s1, 57
	s_add_i32 s0, s24, 8
	s_cmp_lt_u32 s0, 17
	v_writelane_b32 v252, s24, 58
	s_cselect_b64 s[0:1], -1, 0
	v_writelane_b32 v252, s0, 59
	s_ashr_i32 s3, s2, 31
	s_cmp_lt_i32 s4, 4
	v_writelane_b32 v252, s1, 60
	v_writelane_b32 v252, s2, 61
	s_mul_i32 s0, s2, 0x108
	s_nop 0
	v_writelane_b32 v252, s3, 62
	v_writelane_b32 v252, s0, 63
	s_mov_b64 s[2:3], 0
	s_nop 0
	v_writelane_b32 v253, s1, 0
	v_writelane_b32 v253, s4, 1
	s_mov_b64 s[4:5], 0
	v_writelane_b32 v253, s4, 2
	s_mov_b64 s[0:1], -1
	s_nop 0
	v_writelane_b32 v253, s5, 3
	s_cbranch_scc1 .LBB0_157
	v_readlane_b32 s0, v253, 1
	s_cmp_gt_i32 s0, 5
	s_cbranch_scc0 .LBB0_27
	s_cmp_gt_i32 s0, 6
	s_cbranch_scc0 .LBB0_28
	s_cmp_eq_u32 s0, 7
	s_mov_b64 s[0:1], -1
	s_cbranch_scc0 .LBB0_33
	v_readlane_b32 s16, v251, 1
	v_readlane_b32 s30, v251, 15
	v_readlane_b32 s31, v251, 16
	v_readlane_b32 s8, v251, 21
	s_mov_b64 s[0:1], s[30:31]
	s_waitcnt vmcnt(0)
	v_mov_b32_e32 v2, v211
	v_readlane_b32 s9, v251, 22
	v_readlane_b32 s10, v252, 34
	v_readlane_b32 s18, v251, 3
	s_load_dword s10, s[8:9], 0x0
	v_readlane_b32 s19, v251, 4
	s_add_u32 s18, s0, 0x1f80000
	v_readlane_b32 s20, v251, 5
	s_addc_u32 s19, s1, 0
	v_readlane_b32 s21, v251, 6
	s_add_u32 s20, s0, 0xf00000
	s_addc_u32 s21, s1, 0
	v_readlane_b32 s11, v252, 35
	v_readlane_b32 s22, v251, 7
	s_add_u32 s4, s0, 0x6080000
	v_and_b32_e32 v0, 15, v2
	s_waitcnt lgkmcnt(0)
	v_writelane_b32 v252, s10, 34
	v_ashrrev_i32_e32 v3, 2, v2
	s_movk_i32 s8, 0xffc0
	v_lshrrev_b32_e32 v2, 2, v2
	s_addc_u32 s5, s1, 0
	v_writelane_b32 v252, s11, 35
	v_and_or_b32 v0, v3, s8, v0
	v_and_b32_e32 v142, 60, v2
	s_mov_b32 s22, 0
	v_readlane_b32 s17, v251, 2
	v_readlane_b32 s23, v251, 8
	v_readlane_b32 s24, v251, 9
	v_readlane_b32 s25, v251, 10
	v_readlane_b32 s26, v251, 11
	v_readlane_b32 s27, v251, 12
	v_readlane_b32 s28, v251, 13
	v_readlane_b32 s29, v251, 14
	s_mov_b32 s100, 0
	s_branch .LBB0_16
.LBB0_14:
	s_or_b64 exec, exec, s[10:11]
	s_mov_b32 s100, 0
	v_readlane_b32 s24, v252, 34
	v_readlane_b32 s25, v251, 0
	s_add_i32 s26, s22, 1
	s_mul_i32 s26, s26, s24
	s_add_u32 s26, s26, s25
	s_cmp_ge_u32 s26, 0xb2c
	s_cbranch_scc1 .Lupf_none
	s_and_b32 s27, s26, 7
	s_lshr_b32 s28, s26, 3
	s_mul_i32 s29, s27, 0x166
	s_mul_i32 s30, s27, 0x165
	s_add_u32 s30, s30, 4
	s_cmp_lt_u32 s27, 4
	s_cselect_b32 s29, s29, s30
	s_add_u32 s29, s29, s28
	s_mul_hi_u32 s30, s29, 0x1745d18
	s_mul_i32 s31, s30, 0xb0
	s_sub_u32 s31, s29, s31
	s_lshl_b32 s32, s30, 3
	s_cmp_eq_u32 s30, 16
	s_cselect_b32 s38, 1, 3
	s_lshl_b32 s39, 1, s38
	s_sub_u32 s39, s39, 1
	s_and_b32 s39, s31, s39
	s_add_u32 s32, s32, s39
	s_lshr_b32 s31, s31, s38
	s_lshl_b32 s32, s32, 19
	s_lshl_b32 s31, s31, 19
	s_add_u32 s42, s18, s32
	s_addc_u32 s43, s19, 0
	s_add_u32 s44, s20, s31
	s_addc_u32 s45, s21, 0
	s_add_u32 s46, s42, 0x40000
	s_addc_u32 s47, s43, 0
	s_add_u32 s48, s44, 0x40000
	s_addc_u32 s49, s45, 0
	v_lshlrev_b32_e32 v144, 4, v219
	v_lshrrev_b32_e32 v145, 5, v219
	v_lshlrev_b32_e32 v145, 5, v145
	v_xor_b32_e32 v144, v144, v145
	v_lshrrev_b32_e32 v145, 6, v211
	v_lshrrev_b32_e32 v146, 1, v145
	v_lshlrev_b32_e32 v146, 4, v146
	v_lshrrev_b32_e32 v147, 6, v144
	v_add_u32_e32 v146, v146, v147
	v_readfirstlane_b32 s50, v145
	v_and_b32_e32 v145, 1, v145
	v_lshlrev_b32_e32 v145, 5, v145
	v_and_b32_e32 v147, 63, v144
	v_lshrrev_b32_e32 v147, 1, v147
	v_add_u32_e32 v145, v145, v147
	v_lshlrev_b32_e32 v146, 11, v146
	v_lshl_add_u32 v146, v145, 1, v146
	v_mov_b32_e32 v147, 0
	v_add_u32_e32 v150, 0x20000, v146
	v_mov_b32_e32 v151, 0
	s_lshl_b32 s50, s50, 10
	s_add_u32 m0, s50, 0x10000
	v_lshl_add_u64 v[148:149], v[146:147], 0, s[44:45]
	s_nop 0
	global_load_lds_dwordx4 v[148:149], off
	s_add_u32 m0, s50, 0x12000
	v_lshl_add_u64 v[152:153], v[150:151], 0, s[44:45]
	s_nop 0
	global_load_lds_dwordx4 v[152:153], off
	s_add_u32 m0, s50, 0x0
	v_lshl_add_u64 v[148:149], v[146:147], 0, s[42:43]
	s_nop 0
	global_load_lds_dwordx4 v[148:149], off
	s_add_u32 m0, s50, 0x2000
	v_lshl_add_u64 v[152:153], v[150:151], 0, s[42:43]
	s_nop 0
	global_load_lds_dwordx4 v[152:153], off
	s_add_u32 m0, s50, 0x14000
	v_lshl_add_u64 v[148:149], v[146:147], 0, s[48:49]
	s_nop 0
	global_load_lds_dwordx4 v[148:149], off
	s_add_u32 m0, s50, 0x16000
	v_lshl_add_u64 v[152:153], v[150:151], 0, s[48:49]
	s_nop 0
	global_load_lds_dwordx4 v[152:153], off
	s_add_u32 m0, s50, 0x4000
	v_lshl_add_u64 v[148:149], v[146:147], 0, s[46:47]
	s_nop 0
	global_load_lds_dwordx4 v[148:149], off
	s_add_u32 m0, s50, 0x6000
	v_lshl_add_u64 v[152:153], v[150:151], 0, s[46:47]
	s_nop 0
	global_load_lds_dwordx4 v[152:153], off
	s_mov_b32 s100, 1
.Lupf_none:
	v_mul_f32_e32 v133, 0xbfb8aa3b, v126
	v_exp_f32_e32 v133, v133
	v_lshl_or_b32 v130, s23, 7, v142
	v_ashrrev_i32_e32 v131, 31, v130
	v_add_u32_e32 v132, s8, v0
	v_add_f32_e32 v133, 1.0, v133
	v_rcp_f32_e32 v134, v133
	v_mul_f32_e32 v133, 0xbfb8aa3b, v127
	v_exp_f32_e32 v133, v133
	v_lshl_add_u64 v[130:131], v[130:131], 1, s[4:5]
	s_movk_i32 s10, 0x1600
	s_add_i32 s22, s22, 1
	v_add_f32_e32 v133, 1.0, v133
	v_rcp_f32_e32 v135, v133
	s_nop 0
	v_pk_mul_f32 v[126:127], v[126:127], v[134:135]
	s_nop 0
	v_pk_mul_f32 v[122:123], v[122:123], v[126:127]
	s_nop 0
	v_cvt_pk_bf16_f32 v126, v122, v123
	v_mul_f32_e32 v122, 0xbfb8aa3b, v128
	v_mul_f32_e32 v123, 0xbfb8aa3b, v129
	v_exp_f32_e32 v122, v122
	v_exp_f32_e32 v123, v123
	v_add_f32_e32 v122, 1.0, v122
	v_add_f32_e32 v123, 1.0, v123
	v_rcp_f32_e32 v122, v122
	v_rcp_f32_e32 v123, v123
	s_nop 0
	v_pk_mul_f32 v[122:123], v[128:129], v[122:123]
	s_nop 0
	v_pk_mul_f32 v[122:123], v[124:125], v[122:123]
	v_mul_f32_e32 v124, 0xbfb8aa3b, v118
	v_mul_f32_e32 v125, 0xbfb8aa3b, v119
	v_exp_f32_e32 v124, v124
	v_exp_f32_e32 v125, v125
	v_cvt_pk_bf16_f32 v127, v122, v123
	v_mad_i64_i32 v[122:123], s[8:9], v132, s10, v[130:131]
	v_add_f32_e32 v124, 1.0, v124
	v_add_f32_e32 v125, 1.0, v125
	v_rcp_f32_e32 v124, v124
	v_rcp_f32_e32 v125, v125
	s_waitcnt vmcnt(0)
	flat_store_dwordx2 v[122:123], v[126:127]
	v_or_b32_e32 v126, 16, v132
	v_pk_mul_f32 v[118:119], v[118:119], v[124:125]
	s_nop 0
	v_pk_mul_f32 v[114:115], v[114:115], v[118:119]
	s_nop 0
	v_cvt_pk_bf16_f32 v118, v114, v115
	v_mul_f32_e32 v114, 0xbfb8aa3b, v120
	v_mul_f32_e32 v115, 0xbfb8aa3b, v121
	v_exp_f32_e32 v114, v114
	v_exp_f32_e32 v115, v115
	v_add_f32_e32 v114, 1.0, v114
	v_add_f32_e32 v115, 1.0, v115
	v_rcp_f32_e32 v114, v114
	v_rcp_f32_e32 v115, v115
	s_nop 0
	v_pk_mul_f32 v[114:115], v[120:121], v[114:115]
	s_nop 0
	v_pk_mul_f32 v[114:115], v[116:117], v[114:115]
	v_mul_f32_e32 v116, 0xbfb8aa3b, v110
	v_mul_f32_e32 v117, 0xbfb8aa3b, v111
	v_exp_f32_e32 v116, v116
	v_exp_f32_e32 v117, v117
	v_cvt_pk_bf16_f32 v119, v114, v115
	v_mad_i64_i32 v[114:115], s[8:9], v126, s10, v[130:131]
	v_add_f32_e32 v116, 1.0, v116
	v_add_f32_e32 v117, 1.0, v117
	v_rcp_f32_e32 v116, v116
	v_rcp_f32_e32 v117, v117
	flat_store_dwordx2 v[114:115], v[118:119]
	v_or_b32_e32 v118, 32, v132
	v_pk_mul_f32 v[110:111], v[110:111], v[116:117]
	s_nop 0
	v_pk_mul_f32 v[106:107], v[106:107], v[110:111]
	s_nop 0
	v_cvt_pk_bf16_f32 v110, v106, v107
	v_mul_f32_e32 v106, 0xbfb8aa3b, v112
	v_mul_f32_e32 v107, 0xbfb8aa3b, v113
	v_exp_f32_e32 v106, v106
	v_exp_f32_e32 v107, v107
	v_add_f32_e32 v106, 1.0, v106
	v_add_f32_e32 v107, 1.0, v107
	v_rcp_f32_e32 v106, v106
	v_rcp_f32_e32 v107, v107
	s_nop 0
	v_pk_mul_f32 v[106:107], v[112:113], v[106:107]
	s_nop 0
	v_pk_mul_f32 v[106:107], v[108:109], v[106:107]
	v_mul_f32_e32 v108, 0xbfb8aa3b, v102
	v_mul_f32_e32 v109, 0xbfb8aa3b, v103
	v_exp_f32_e32 v108, v108
	v_exp_f32_e32 v109, v109
	v_cvt_pk_bf16_f32 v111, v106, v107
	v_mad_i64_i32 v[106:107], s[8:9], v118, s10, v[130:131]
	v_add_f32_e32 v108, 1.0, v108
	v_add_f32_e32 v109, 1.0, v109
	v_rcp_f32_e32 v108, v108
	v_rcp_f32_e32 v109, v109
	flat_store_dwordx2 v[106:107], v[110:111]
	v_or_b32_e32 v110, 48, v132
	v_pk_mul_f32 v[102:103], v[102:103], v[108:109]
	s_nop 0
	v_pk_mul_f32 v[98:99], v[98:99], v[102:103]
	s_nop 0
	v_cvt_pk_bf16_f32 v102, v98, v99
	v_mul_f32_e32 v98, 0xbfb8aa3b, v104
	v_mul_f32_e32 v99, 0xbfb8aa3b, v105
	v_exp_f32_e32 v98, v98
	v_exp_f32_e32 v99, v99
	v_add_f32_e32 v98, 1.0, v98
	v_add_f32_e32 v99, 1.0, v99
	v_rcp_f32_e32 v98, v98
	v_rcp_f32_e32 v99, v99
	s_nop 0
	v_pk_mul_f32 v[98:99], v[104:105], v[98:99]
	s_nop 0
	v_pk_mul_f32 v[98:99], v[100:101], v[98:99]
	v_mul_f32_e32 v100, 0xbfb8aa3b, v94
	v_mul_f32_e32 v101, 0xbfb8aa3b, v95
	v_exp_f32_e32 v100, v100
	v_exp_f32_e32 v101, v101
	v_cvt_pk_bf16_f32 v103, v98, v99
	v_mad_i64_i32 v[98:99], s[8:9], v110, s10, v[130:131]
	v_add_f32_e32 v100, 1.0, v100
	v_add_f32_e32 v101, 1.0, v101
	v_rcp_f32_e32 v100, v100
	v_rcp_f32_e32 v101, v101
	flat_store_dwordx2 v[98:99], v[102:103]
	v_pk_mul_f32 v[94:95], v[94:95], v[100:101]
	s_nop 0
	v_pk_mul_f32 v[90:91], v[90:91], v[94:95]
	s_nop 0
	v_cvt_pk_bf16_f32 v90, v90, v91
	v_mul_f32_e32 v91, 0xbfb8aa3b, v96
	v_exp_f32_e32 v91, v91
	s_nop 0
	v_add_f32_e32 v91, 1.0, v91
	v_rcp_f32_e32 v94, v91
	v_mul_f32_e32 v91, 0xbfb8aa3b, v97
	v_exp_f32_e32 v91, v91
	s_nop 0
	v_add_f32_e32 v91, 1.0, v91
	v_rcp_f32_e32 v95, v91
	s_nop 0
	v_pk_mul_f32 v[94:95], v[96:97], v[94:95]
	s_nop 0
	v_pk_mul_f32 v[92:93], v[92:93], v[94:95]
	s_nop 0
	v_cvt_pk_bf16_f32 v91, v92, v93
	flat_store_dwordx2 v[122:123], v[90:91] offset:128
	v_mul_f32_e32 v90, 0xbfb8aa3b, v86
	v_mul_f32_e32 v91, 0xbfb8aa3b, v87
	v_exp_f32_e32 v90, v90
	v_exp_f32_e32 v91, v91
	v_add_f32_e32 v90, 1.0, v90
	v_add_f32_e32 v91, 1.0, v91
	v_rcp_f32_e32 v90, v90
	v_rcp_f32_e32 v91, v91
	s_nop 0
	v_pk_mul_f32 v[86:87], v[86:87], v[90:91]
	s_nop 0
	v_pk_mul_f32 v[82:83], v[82:83], v[86:87]
	s_nop 0
	v_cvt_pk_bf16_f32 v82, v82, v83
	v_mul_f32_e32 v83, 0xbfb8aa3b, v88
	v_exp_f32_e32 v83, v83
	s_nop 0
	v_add_f32_e32 v83, 1.0, v83
	v_rcp_f32_e32 v86, v83
	v_mul_f32_e32 v83, 0xbfb8aa3b, v89
	v_exp_f32_e32 v83, v83
	s_nop 0
	v_add_f32_e32 v83, 1.0, v83
	v_rcp_f32_e32 v87, v83
	s_nop 0
	v_pk_mul_f32 v[86:87], v[88:89], v[86:87]
	s_nop 0
	v_pk_mul_f32 v[84:85], v[84:85], v[86:87]
	s_nop 0
	v_cvt_pk_bf16_f32 v83, v84, v85
	flat_store_dwordx2 v[114:115], v[82:83] offset:128
	v_mul_f32_e32 v82, 0xbfb8aa3b, v78
	v_mul_f32_e32 v83, 0xbfb8aa3b, v79
	v_exp_f32_e32 v82, v82
	v_exp_f32_e32 v83, v83
	v_add_f32_e32 v82, 1.0, v82
	v_add_f32_e32 v83, 1.0, v83
	v_rcp_f32_e32 v82, v82
	v_rcp_f32_e32 v83, v83
	s_nop 0
	v_pk_mul_f32 v[78:79], v[78:79], v[82:83]
	s_nop 0
	v_pk_mul_f32 v[74:75], v[74:75], v[78:79]
	s_nop 0
	v_cvt_pk_bf16_f32 v74, v74, v75
	v_mul_f32_e32 v75, 0xbfb8aa3b, v80
	v_exp_f32_e32 v75, v75
	s_nop 0
	v_add_f32_e32 v75, 1.0, v75
	v_rcp_f32_e32 v78, v75
	v_mul_f32_e32 v75, 0xbfb8aa3b, v81
	v_exp_f32_e32 v75, v75
	s_nop 0
	v_add_f32_e32 v75, 1.0, v75
	v_rcp_f32_e32 v79, v75
	s_nop 0
	v_pk_mul_f32 v[78:79], v[80:81], v[78:79]
	s_nop 0
	v_pk_mul_f32 v[76:77], v[76:77], v[78:79]
	s_nop 0
	v_cvt_pk_bf16_f32 v75, v76, v77
	flat_store_dwordx2 v[106:107], v[74:75] offset:128
	v_mul_f32_e32 v74, 0xbfb8aa3b, v70
	v_mul_f32_e32 v75, 0xbfb8aa3b, v71
	v_exp_f32_e32 v74, v74
	v_exp_f32_e32 v75, v75
	v_add_f32_e32 v74, 1.0, v74
	v_add_f32_e32 v75, 1.0, v75
	v_rcp_f32_e32 v74, v74
	v_rcp_f32_e32 v75, v75
	s_nop 0
	v_pk_mul_f32 v[70:71], v[70:71], v[74:75]
	s_nop 0
	v_pk_mul_f32 v[66:67], v[66:67], v[70:71]
	s_nop 0
	v_cvt_pk_bf16_f32 v66, v66, v67
	v_mul_f32_e32 v67, 0xbfb8aa3b, v72
	v_exp_f32_e32 v67, v67
	s_nop 0
	v_add_f32_e32 v67, 1.0, v67
	v_rcp_f32_e32 v70, v67
	v_mul_f32_e32 v67, 0xbfb8aa3b, v73
	v_exp_f32_e32 v67, v67
	s_nop 0
	v_add_f32_e32 v67, 1.0, v67
	v_rcp_f32_e32 v71, v67
	s_nop 0
	v_pk_mul_f32 v[70:71], v[72:73], v[70:71]
	s_nop 0
	v_pk_mul_f32 v[68:69], v[68:69], v[70:71]
	s_nop 0
	v_cvt_pk_bf16_f32 v67, v68, v69
	flat_store_dwordx2 v[98:99], v[66:67] offset:128
	v_mul_f32_e32 v66, 0xbfb8aa3b, v62
	v_mul_f32_e32 v67, 0xbfb8aa3b, v63
	v_exp_f32_e32 v66, v66
	v_exp_f32_e32 v67, v67
	v_add_u32_e32 v68, 0x80, v132
	v_add_f32_e32 v66, 1.0, v66
	v_add_f32_e32 v67, 1.0, v67
	v_rcp_f32_e32 v66, v66
	v_rcp_f32_e32 v67, v67
	s_nop 0
	v_pk_mul_f32 v[62:63], v[62:63], v[66:67]
	s_nop 0
	v_pk_mul_f32 v[58:59], v[58:59], v[62:63]
	s_nop 0
	v_cvt_pk_bf16_f32 v62, v58, v59
	v_mul_f32_e32 v58, 0xbfb8aa3b, v64
	v_mul_f32_e32 v59, 0xbfb8aa3b, v65
	v_exp_f32_e32 v58, v58
	v_exp_f32_e32 v59, v59
	v_add_f32_e32 v58, 1.0, v58
	v_add_f32_e32 v59, 1.0, v59
	v_rcp_f32_e32 v58, v58
	v_rcp_f32_e32 v59, v59
	s_nop 0
	v_pk_mul_f32 v[58:59], v[64:65], v[58:59]
	s_nop 0
	v_pk_mul_f32 v[58:59], v[60:61], v[58:59]
	v_mul_f32_e32 v60, 0xbfb8aa3b, v54
	v_mul_f32_e32 v61, 0xbfb8aa3b, v55
	v_exp_f32_e32 v60, v60
	v_exp_f32_e32 v61, v61
	v_cvt_pk_bf16_f32 v63, v58, v59
	v_mad_i64_i32 v[58:59], s[8:9], v68, s10, v[130:131]
	v_add_f32_e32 v60, 1.0, v60
	v_add_f32_e32 v61, 1.0, v61
	v_rcp_f32_e32 v60, v60
	v_rcp_f32_e32 v61, v61
	flat_store_dwordx2 v[58:59], v[62:63]
	v_add_u32_e32 v62, 0x90, v132
	v_pk_mul_f32 v[54:55], v[54:55], v[60:61]
	s_nop 0
	v_pk_mul_f32 v[50:51], v[50:51], v[54:55]
	s_nop 0
	v_cvt_pk_bf16_f32 v54, v50, v51
	v_mul_f32_e32 v50, 0xbfb8aa3b, v56
	v_mul_f32_e32 v51, 0xbfb8aa3b, v57
	v_exp_f32_e32 v50, v50
	v_exp_f32_e32 v51, v51
	v_add_f32_e32 v50, 1.0, v50
	v_add_f32_e32 v51, 1.0, v51
	v_rcp_f32_e32 v50, v50
	v_rcp_f32_e32 v51, v51
	s_nop 0
	v_pk_mul_f32 v[50:51], v[56:57], v[50:51]
	s_nop 0
	v_pk_mul_f32 v[50:51], v[52:53], v[50:51]
	v_mul_f32_e32 v52, 0xbfb8aa3b, v46
	v_mul_f32_e32 v53, 0xbfb8aa3b, v47
	v_exp_f32_e32 v52, v52
	v_exp_f32_e32 v53, v53
	v_cvt_pk_bf16_f32 v55, v50, v51
	v_mad_i64_i32 v[50:51], s[8:9], v62, s10, v[130:131]
	v_add_f32_e32 v52, 1.0, v52
	v_add_f32_e32 v53, 1.0, v53
	v_rcp_f32_e32 v52, v52
	v_rcp_f32_e32 v53, v53
	flat_store_dwordx2 v[50:51], v[54:55]
	v_add_u32_e32 v54, 0xa0, v132
	v_pk_mul_f32 v[46:47], v[46:47], v[52:53]
	s_nop 0
	v_pk_mul_f32 v[42:43], v[42:43], v[46:47]
	s_nop 0
	v_cvt_pk_bf16_f32 v46, v42, v43
	v_mul_f32_e32 v42, 0xbfb8aa3b, v48
	v_mul_f32_e32 v43, 0xbfb8aa3b, v49
	v_exp_f32_e32 v42, v42
	v_exp_f32_e32 v43, v43
	v_add_f32_e32 v42, 1.0, v42
	v_add_f32_e32 v43, 1.0, v43
	v_rcp_f32_e32 v42, v42
	v_rcp_f32_e32 v43, v43
	s_nop 0
	v_pk_mul_f32 v[42:43], v[48:49], v[42:43]
	s_nop 0
	v_pk_mul_f32 v[42:43], v[44:45], v[42:43]
	v_mul_f32_e32 v44, 0xbfb8aa3b, v38
	v_mul_f32_e32 v45, 0xbfb8aa3b, v39
	v_exp_f32_e32 v44, v44
	v_exp_f32_e32 v45, v45
	v_cvt_pk_bf16_f32 v47, v42, v43
	v_mad_i64_i32 v[42:43], s[8:9], v54, s10, v[130:131]
	v_add_f32_e32 v44, 1.0, v44
	v_add_f32_e32 v45, 1.0, v45
	v_rcp_f32_e32 v44, v44
	v_rcp_f32_e32 v45, v45
	flat_store_dwordx2 v[42:43], v[46:47]
	v_add_u32_e32 v46, 0xb0, v132
	v_pk_mul_f32 v[38:39], v[38:39], v[44:45]
	s_nop 0
	v_pk_mul_f32 v[34:35], v[34:35], v[38:39]
	s_nop 0
	v_cvt_pk_bf16_f32 v38, v34, v35
	v_mul_f32_e32 v34, 0xbfb8aa3b, v40
	v_mul_f32_e32 v35, 0xbfb8aa3b, v41
	v_exp_f32_e32 v34, v34
	v_exp_f32_e32 v35, v35
	v_add_f32_e32 v34, 1.0, v34
	v_add_f32_e32 v35, 1.0, v35
	v_rcp_f32_e32 v34, v34
	v_rcp_f32_e32 v35, v35
	s_nop 0
	v_pk_mul_f32 v[34:35], v[40:41], v[34:35]
	s_nop 0
	v_pk_mul_f32 v[34:35], v[36:37], v[34:35]
	v_mul_f32_e32 v36, 0xbfb8aa3b, v30
	v_mul_f32_e32 v37, 0xbfb8aa3b, v31
	v_exp_f32_e32 v36, v36
	v_exp_f32_e32 v37, v37
	v_cvt_pk_bf16_f32 v39, v34, v35
	v_mad_i64_i32 v[34:35], s[8:9], v46, s10, v[130:131]
	v_add_f32_e32 v36, 1.0, v36
	v_add_f32_e32 v37, 1.0, v37
	v_rcp_f32_e32 v36, v36
	v_rcp_f32_e32 v37, v37
	s_mov_b64 s[10:11], 0
	flat_store_dwordx2 v[34:35], v[38:39]
	v_pk_mul_f32 v[30:31], v[30:31], v[36:37]
	s_nop 0
	v_pk_mul_f32 v[26:27], v[26:27], v[30:31]
	s_nop 0
	v_cvt_pk_bf16_f32 v26, v26, v27
	v_mul_f32_e32 v27, 0xbfb8aa3b, v32
	v_exp_f32_e32 v27, v27
	s_nop 0
	v_add_f32_e32 v27, 1.0, v27
	v_rcp_f32_e32 v30, v27
	v_mul_f32_e32 v27, 0xbfb8aa3b, v33
	v_exp_f32_e32 v27, v27
	s_nop 0
	v_add_f32_e32 v27, 1.0, v27
	v_rcp_f32_e32 v31, v27
	s_nop 0
	v_pk_mul_f32 v[30:31], v[32:33], v[30:31]
	s_nop 0
	v_pk_mul_f32 v[28:29], v[28:29], v[30:31]
	s_nop 0
	v_cvt_pk_bf16_f32 v27, v28, v29
	flat_store_dwordx2 v[58:59], v[26:27] offset:128
	v_mul_f32_e32 v26, 0xbfb8aa3b, v22
	v_mul_f32_e32 v27, 0xbfb8aa3b, v23
	v_exp_f32_e32 v26, v26
	v_exp_f32_e32 v27, v27
	v_add_f32_e32 v26, 1.0, v26
	v_add_f32_e32 v27, 1.0, v27
	v_rcp_f32_e32 v26, v26
	v_rcp_f32_e32 v27, v27
	s_nop 0
	v_pk_mul_f32 v[22:23], v[22:23], v[26:27]
	s_nop 0
	v_pk_mul_f32 v[18:19], v[18:19], v[22:23]
	s_nop 0
	v_cvt_pk_bf16_f32 v18, v18, v19
	v_mul_f32_e32 v19, 0xbfb8aa3b, v24
	v_exp_f32_e32 v19, v19
	s_nop 0
	v_add_f32_e32 v19, 1.0, v19
	v_rcp_f32_e32 v22, v19
	v_mul_f32_e32 v19, 0xbfb8aa3b, v25
	v_exp_f32_e32 v19, v19
	s_nop 0
	v_add_f32_e32 v19, 1.0, v19
	v_rcp_f32_e32 v23, v19
	s_nop 0
	v_pk_mul_f32 v[22:23], v[24:25], v[22:23]
	s_nop 0
	v_pk_mul_f32 v[20:21], v[20:21], v[22:23]
	s_nop 0
	v_cvt_pk_bf16_f32 v19, v20, v21
	flat_store_dwordx2 v[50:51], v[18:19] offset:128
	v_mul_f32_e32 v18, 0xbfb8aa3b, v14
	v_mul_f32_e32 v19, 0xbfb8aa3b, v15
	v_exp_f32_e32 v18, v18
	v_exp_f32_e32 v19, v19
	v_add_f32_e32 v18, 1.0, v18
	v_add_f32_e32 v19, 1.0, v19
	v_rcp_f32_e32 v18, v18
	v_rcp_f32_e32 v19, v19
	s_nop 0
	v_pk_mul_f32 v[14:15], v[14:15], v[18:19]
	s_nop 0
	v_pk_mul_f32 v[10:11], v[10:11], v[14:15]
	s_nop 0
	v_cvt_pk_bf16_f32 v10, v10, v11
	v_mul_f32_e32 v11, 0xbfb8aa3b, v16
	v_exp_f32_e32 v11, v11
	s_nop 0
	v_add_f32_e32 v11, 1.0, v11
	v_rcp_f32_e32 v14, v11
	v_mul_f32_e32 v11, 0xbfb8aa3b, v17
	v_exp_f32_e32 v11, v11
	s_nop 0
	v_add_f32_e32 v11, 1.0, v11
	v_rcp_f32_e32 v15, v11
	s_nop 0
	v_pk_mul_f32 v[14:15], v[16:17], v[14:15]
	s_nop 0
	v_pk_mul_f32 v[12:13], v[12:13], v[14:15]
	s_nop 0
	v_cvt_pk_bf16_f32 v11, v12, v13
	flat_store_dwordx2 v[42:43], v[10:11] offset:128
	v_mul_f32_e32 v10, 0xbfb8aa3b, v6
	v_mul_f32_e32 v11, 0xbfb8aa3b, v7
	v_exp_f32_e32 v10, v10
	v_exp_f32_e32 v11, v11
	v_add_f32_e32 v10, 1.0, v10
	v_add_f32_e32 v11, 1.0, v11
	v_rcp_f32_e32 v10, v10
	v_rcp_f32_e32 v11, v11
	s_nop 0
	v_pk_mul_f32 v[6:7], v[6:7], v[10:11]
	s_nop 0
	v_pk_mul_f32 v[2:3], v[2:3], v[6:7]
	s_nop 0
	v_cvt_pk_bf16_f32 v2, v2, v3
	v_mul_f32_e32 v3, 0xbfb8aa3b, v8
	v_exp_f32_e32 v3, v3
	s_nop 0
	v_add_f32_e32 v3, 1.0, v3
	v_rcp_f32_e32 v6, v3
	v_mul_f32_e32 v3, 0xbfb8aa3b, v9
	v_exp_f32_e32 v3, v3
	s_nop 0
	v_add_f32_e32 v3, 1.0, v3
	v_rcp_f32_e32 v7, v3
	s_nop 0
	v_pk_mul_f32 v[6:7], v[8:9], v[6:7]
	s_nop 0
	v_pk_mul_f32 v[4:5], v[4:5], v[6:7]
	s_nop 0
	v_cvt_pk_bf16_f32 v3, v4, v5
	flat_store_dwordx2 v[34:35], v[2:3] offset:128

.LBB0_21:
	s_add_i32 s8, s11, s8
	s_mul_hi_i32 s9, s8, 0x2e8ba2e9
	s_lshr_b32 s10, s9, 31
	s_ashr_i32 s9, s9, 5
	s_add_i32 s9, s9, s10
	s_lshl_b32 s10, s9, 3
	s_sub_i32 s11, 0x82, s10
	s_min_i32 s11, s11, 8
	s_abs_i32 s13, s11
	v_cvt_f32_u32_e32 v2, s13
	s_sub_i32 s16, 0, s13
	s_mulk_i32 s9, 0xb0
	s_sub_i32 s8, s8, s9
	v_rcp_iflag_f32_e32 v2, v2
	v_mov_b32_e32 v143, v211
	s_abs_i32 s12, s8
	v_mul_f32_e32 v2, 0x4f7ffffe, v2
	v_cvt_u32_f32_e32 v2, v2
	s_xor_b32 s9, s8, s11
	s_ashr_i32 s9, s9, 31
	v_lshlrev_b32_e32 v22, 4, v143
	v_readfirstlane_b32 s17, v2
	s_mul_i32 s16, s16, s17
	s_mul_hi_u32 s16, s17, s16
	s_add_i32 s17, s17, s16
	v_ashrrev_i32_e32 v2, 31, v143
	s_mul_hi_u32 s16, s12, s17
	v_lshrrev_b32_e32 v2, 26, v2
	s_mul_i32 s17, s16, s13
	v_add_u32_e32 v2, v143, v2
	s_sub_i32 s12, s12, s17
	v_ashrrev_i32_e32 v3, 6, v2
	v_bfe_i32 v2, v143, 27, 1
	s_add_i32 s17, s16, 1
	s_sub_i32 s23, s12, s13
	v_lshrrev_b32_e32 v2, 22, v2
	s_cmp_ge_u32 s12, s13
	v_add_u32_e32 v2, v22, v2
	s_cselect_b32 s16, s17, s16
	v_and_b32_e32 v2, 0xfffffc00, v2
	s_cselect_b32 s12, s23, s12
	s_add_i32 s17, s16, 1
	v_sub_u32_e32 v2, v22, v2
	s_cmp_ge_u32 s12, s13
	v_lshrrev_b32_e32 v4, 4, v2
	s_cselect_b32 s12, s17, s16
	v_bitop3_b32 v4, v4, v2, 32 bitop3:0x6c
	v_ashrrev_i32_e32 v2, 31, v2
	s_xor_b32 s12, s12, s9
	v_lshrrev_b32_e32 v2, 26, v2
	s_sub_i32 s23, s12, s9
	v_lshlrev_b32_e32 v5, 3, v3
	v_add_u32_e32 v2, v4, v2
	s_mul_i32 s9, s23, s11
	v_and_b32_e32 v5, -16, v5
	v_ashrrev_i32_e32 v6, 6, v2
	s_sub_i32 s8, s8, s9
	s_lshl_b32 s16, s23, 8
	v_add_u32_e32 v2, v6, v5
	v_mul_i32_i24_e32 v5, 64, v6
	s_add_i32 s10, s10, s8
	s_ashr_i32 s17, s16, 31
	v_lshlrev_b32_e32 v3, 5, v3
	v_sub_u32_e32 v4, v4, v5
	s_lshl_b32 s8, s10, 8
	s_lshl_b64 s[10:11], s[16:17], 11
	v_and_b32_e32 v3, 32, v3
	v_ashrrev_i16_sdwa v4, v213, sext(v4) dst_sel:DWORD dst_unused:UNUSED_PAD src0_sel:DWORD src1_sel:BYTE_0
	s_add_u32 s12, s20, s10
	v_add_u32_sdwa v4, v3, sext(v4) dst_sel:DWORD dst_unused:UNUSED_PAD src0_sel:DWORD src1_sel:WORD_0
	v_ashrrev_i32_e32 v3, 31, v2
	s_addc_u32 s13, s21, s11
	v_lshlrev_b64 v[2:3], 11, v[2:3]
	v_ashrrev_i32_e32 v5, 31, v4
	v_lshl_add_u64 v[6:7], s[12:13], 0, v[2:3]
	v_lshlrev_b64 v[4:5], 1, v[4:5]
	v_add_u32_e32 v24, 0x2000, v22
	v_lshl_add_u64 v[10:11], v[6:7], 0, v[4:5]
	v_ashrrev_i32_e32 v6, 31, v24
	v_lshrrev_b32_e32 v6, 22, v6
	v_add_u32_e32 v6, v24, v6
	v_ashrrev_i32_e32 v7, 10, v6
	v_mul_i32_i24_e32 v6, 0x400, v7
	v_sub_u32_e32 v6, v24, v6
	v_lshrrev_b32_e32 v8, 4, v6
	v_bitop3_b32 v8, v8, v6, 32 bitop3:0x6c
	v_ashrrev_i32_e32 v9, 31, v8
	v_lshrrev_b32_e32 v9, 26, v9
	v_add_u32_e32 v9, v8, v9
	v_readlane_b32 s17, v252, 21
	v_lshlrev_b32_e32 v6, 3, v7
	v_ashrrev_i32_e32 v12, 6, v9
	v_and_b32_e32 v9, 0xc0, v9
	v_add_u32_e32 v144, s17, v22
	v_and_b32_e32 v6, -16, v6
	v_lshlrev_b32_e32 v7, 5, v7
	v_sub_u32_e32 v8, v8, v9
	v_readfirstlane_b32 s9, v144
	v_add_u32_e32 v6, v12, v6
	v_and_b32_e32 v7, 32, v7
	v_ashrrev_i16_sdwa v8, v213, sext(v8) dst_sel:DWORD dst_unused:UNUSED_PAD src0_sel:DWORD src1_sel:BYTE_0
	v_add_u32_e32 v14, s17, v24
	s_waitcnt vmcnt(0)
	s_mov_b32 m0, s9
	v_add_u32_sdwa v8, v7, sext(v8) dst_sel:DWORD dst_unused:UNUSED_PAD src0_sel:DWORD src1_sel:WORD_0
	v_ashrrev_i32_e32 v7, 31, v6
	v_readfirstlane_b32 s9, v14
	s_waitcnt lgkmcnt(0)
	s_barrier
	s_cmp_eq_u32 s100, 0
	s_cselect_b64 s[52:53], -1, 0
	s_mov_b64 exec, s[52:53]
	global_load_lds_dwordx4 v[10:11], off
	s_mov_b64 exec, -1
	v_lshlrev_b64 v[6:7], 11, v[6:7]
	s_mov_b32 m0, s9
	s_ashr_i32 s9, s8, 31
	v_lshl_add_u64 v[12:13], s[12:13], 0, v[6:7]
	s_lshl_b64 s[12:13], s[8:9], 11
	s_add_u32 s24, s18, s12
	s_addc_u32 s25, s19, s13
	s_bitset1_b32 s16, 7
	s_ashr_i32 s17, s16, 31
	s_lshl_b64 s[16:17], s[16:17], 11
	s_add_u32 s16, s20, s16
	v_ashrrev_i32_e32 v9, 31, v8
	s_addc_u32 s17, s21, s17
	v_lshlrev_b64 v[8:9], 1, v[8:9]
	v_add_u32_e32 v152, 0, v22
	v_lshl_add_u64 v[18:19], s[16:17], 0, v[2:3]
	v_lshl_add_u64 v[20:21], s[16:17], 0, v[6:7]
	s_or_b32 s16, s8, 0x80
	v_lshl_add_u64 v[12:13], v[12:13], 0, v[8:9]
	v_lshl_add_u64 v[14:15], s[24:25], 0, v[2:3]
	v_readfirstlane_b32 s9, v152
	v_lshl_add_u64 v[16:17], s[24:25], 0, v[6:7]
	v_add_u32_e32 v153, 0x2000, v152
	v_readlane_b32 s24, v252, 22
	s_ashr_i32 s17, s16, 31
	s_mov_b64 exec, s[52:53]
	global_load_lds_dwordx4 v[12:13], off
	s_mov_b64 exec, -1
	v_lshl_add_u64 v[14:15], v[14:15], 0, v[4:5]
	s_mov_b32 m0, s9
	v_readfirstlane_b32 s9, v153
	v_add_u32_e32 v155, s24, v22
	s_lshl_b64 s[16:17], s[16:17], 11
	s_mov_b64 exec, s[52:53]
	global_load_lds_dwordx4 v[14:15], off
	s_mov_b64 exec, -1
	v_lshl_add_u64 v[16:17], v[16:17], 0, v[8:9]
	s_mov_b32 m0, s9
	v_readfirstlane_b32 s9, v155
	v_add_u32_e32 v24, s24, v24
	s_add_u32 s16, s18, s16
	s_mov_b64 exec, s[52:53]
	global_load_lds_dwordx4 v[16:17], off
	s_mov_b64 exec, -1
	v_lshl_add_u64 v[18:19], v[18:19], 0, v[4:5]
	s_mov_b32 m0, s9
	v_readfirstlane_b32 s9, v24
	s_addc_u32 s17, s19, s17
	v_add_u32_e32 v156, 0x4000, v152
	s_mov_b64 exec, s[52:53]
	global_load_lds_dwordx4 v[18:19], off
	s_mov_b64 exec, -1
	v_lshl_add_u64 v[20:21], v[20:21], 0, v[8:9]
	s_mov_b32 m0, s9
	v_lshl_add_u64 v[24:25], s[16:17], 0, v[2:3]
	v_readfirstlane_b32 s9, v156
	v_add_u32_e32 v157, 0x6000, v152
	s_mov_b64 exec, s[52:53]
	global_load_lds_dwordx4 v[20:21], off
	s_mov_b64 exec, -1
	v_lshl_add_u64 v[130:131], v[24:25], 0, v[4:5]
	s_mov_b32 m0, s9
	v_lshl_add_u64 v[24:25], s[16:17], 0, v[6:7]
	v_readfirstlane_b32 s9, v157
	s_mov_b64 exec, s[52:53]
	global_load_lds_dwordx4 v[130:131], off
	s_mov_b64 exec, -1
	v_lshl_add_u64 v[132:133], v[24:25], 0, v[8:9]
	s_mov_b32 m0, s9
	v_ashrrev_i32_e32 v23, 8, v143
	s_mov_b64 exec, s[52:53]
	global_load_lds_dwordx4 v[132:133], off
	s_mov_b64 exec, -1
	s_mov_b32 s100, 0
	v_cmp_eq_u32_e32 vcc, 1, v23
	s_and_saveexec_b64 s[16:17], vcc
	s_cbranch_execz .LBB0_23
	s_barrier
